# G2 final epilogue in the quad-contiguous lane layout: accumulators moved by ds_bpermute, gate reads / bf16 writes as 8-byte quads, two row groups of gate reads in flight
# speedup vs baseline: 1.0024x; 1.0024x over previous
.LBB0_1087:
	v_lshrrev_b32_e32 v166, 2, v186
	v_and_b32_e32 v167, 3, v186
	v_and_b32_e32 v168, -16, v151
	v_add_u32_e32 v168, v168, v166
	v_and_b32_e32 v169, -13, v136
	v_lshl_or_b32 v169, v167, 2, v169
	v_or_b32_e32 v169, s13, v169
	v_mul_u32_u24_e32 v171, 0x1320, v168
	v_add_lshl_u32 v171, v171, v169, 1
	v_lshl_add_u32 v172, v168, 10, v169
	v_lshlrev_b32_e32 v172, 1, v172
	v_lshl_add_u32 v170, v167, 4, v166
	v_lshlrev_b32_e32 v170, 2, v170
	v_mov_b32_e32 v173, v171
	global_load_dwordx2 v[198:199], v173, s[8:9]
	global_load_dwordx2 v[200:201], v173, s[8:9] offset:32
	global_load_dwordx2 v[202:203], v173, s[8:9] offset:256
	global_load_dwordx2 v[204:205], v173, s[8:9] offset:288
	v_add_u32_e32 v174, 0x26400, v171
	global_load_dwordx2 v[206:207], v174, s[8:9]
	global_load_dwordx2 v[208:209], v174, s[8:9] offset:32
	global_load_dwordx2 v[210:211], v174, s[8:9] offset:256
	global_load_dwordx2 v[212:213], v174, s[8:9] offset:288
	s_nop 7
	s_nop 7
	ds_bpermute_b32 v128, v170, v128
	ds_bpermute_b32 v129, v170, v129
	ds_bpermute_b32 v130, v170, v130
	ds_bpermute_b32 v131, v170, v131
	ds_bpermute_b32 v124, v170, v124
	ds_bpermute_b32 v125, v170, v125
	ds_bpermute_b32 v126, v170, v126
	ds_bpermute_b32 v127, v170, v127
	ds_bpermute_b32 v120, v170, v120
	ds_bpermute_b32 v121, v170, v121
	ds_bpermute_b32 v122, v170, v122
	ds_bpermute_b32 v123, v170, v123
	ds_bpermute_b32 v116, v170, v116
	ds_bpermute_b32 v117, v170, v117
	ds_bpermute_b32 v118, v170, v118
	ds_bpermute_b32 v119, v170, v119
	s_waitcnt vmcnt(4) lgkmcnt(0)
	v_lshlrev_b32_e32 v214, 16, v198
	v_and_b32_e32 v215, 0xffff0000, v198
	v_lshlrev_b32_e32 v216, 16, v199
	v_and_b32_e32 v217, 0xffff0000, v199
	v_lshlrev_b32_e32 v218, 16, v200
	v_and_b32_e32 v219, 0xffff0000, v200
	v_lshlrev_b32_e32 v220, 16, v201
	v_and_b32_e32 v221, 0xffff0000, v201
	v_lshlrev_b32_e32 v222, 16, v202
	v_and_b32_e32 v223, 0xffff0000, v202
	v_lshlrev_b32_e32 v224, 16, v203
	v_and_b32_e32 v225, 0xffff0000, v203
	v_lshlrev_b32_e32 v226, 16, v204
	v_and_b32_e32 v227, 0xffff0000, v204
	v_lshlrev_b32_e32 v228, 16, v205
	v_and_b32_e32 v229, 0xffff0000, v205
	v_add_u32_e32 v175, 0x4c800, v171
	global_load_dwordx2 v[198:199], v175, s[8:9]
	global_load_dwordx2 v[200:201], v175, s[8:9] offset:32
	global_load_dwordx2 v[202:203], v175, s[8:9] offset:256
	global_load_dwordx2 v[204:205], v175, s[8:9] offset:288
	ds_bpermute_b32 v112, v170, v112
	ds_bpermute_b32 v113, v170, v113
	ds_bpermute_b32 v114, v170, v114
	ds_bpermute_b32 v115, v170, v115
	ds_bpermute_b32 v108, v170, v108
	ds_bpermute_b32 v109, v170, v109
	ds_bpermute_b32 v110, v170, v110
	ds_bpermute_b32 v111, v170, v111
	ds_bpermute_b32 v104, v170, v104
	ds_bpermute_b32 v105, v170, v105
	ds_bpermute_b32 v106, v170, v106
	ds_bpermute_b32 v107, v170, v107
	ds_bpermute_b32 v100, v170, v100
	ds_bpermute_b32 v101, v170, v101
	ds_bpermute_b32 v102, v170, v102
	ds_bpermute_b32 v103, v170, v103
	v_mul_f32_e32 v214, 0xbfb8aa3b, v214
	v_mul_f32_e32 v215, 0xbfb8aa3b, v215
	v_mul_f32_e32 v216, 0xbfb8aa3b, v216
	v_mul_f32_e32 v217, 0xbfb8aa3b, v217
	v_mul_f32_e32 v218, 0xbfb8aa3b, v218
	v_mul_f32_e32 v219, 0xbfb8aa3b, v219
	v_mul_f32_e32 v220, 0xbfb8aa3b, v220
	v_mul_f32_e32 v221, 0xbfb8aa3b, v221
	v_mul_f32_e32 v222, 0xbfb8aa3b, v222
	v_mul_f32_e32 v223, 0xbfb8aa3b, v223
	v_mul_f32_e32 v224, 0xbfb8aa3b, v224
	v_mul_f32_e32 v225, 0xbfb8aa3b, v225
	v_mul_f32_e32 v226, 0xbfb8aa3b, v226
	v_mul_f32_e32 v227, 0xbfb8aa3b, v227
	v_mul_f32_e32 v228, 0xbfb8aa3b, v228
	v_mul_f32_e32 v229, 0xbfb8aa3b, v229
	v_exp_f32_e32 v214, v214
	v_exp_f32_e32 v215, v215
	v_exp_f32_e32 v216, v216
	v_exp_f32_e32 v217, v217
	v_exp_f32_e32 v218, v218
	v_exp_f32_e32 v219, v219
	v_exp_f32_e32 v220, v220
	v_exp_f32_e32 v221, v221
	v_exp_f32_e32 v222, v222
	v_exp_f32_e32 v223, v223
	v_exp_f32_e32 v224, v224
	v_exp_f32_e32 v225, v225
	v_exp_f32_e32 v226, v226
	v_exp_f32_e32 v227, v227
	v_exp_f32_e32 v228, v228
	v_exp_f32_e32 v229, v229
	v_min_f32_e32 v214, 0x7149f2ca, v214
	v_min_f32_e32 v215, 0x7149f2ca, v215
	v_min_f32_e32 v216, 0x7149f2ca, v216
	v_min_f32_e32 v217, 0x7149f2ca, v217
	v_min_f32_e32 v218, 0x7149f2ca, v218
	v_min_f32_e32 v219, 0x7149f2ca, v219
	v_min_f32_e32 v220, 0x7149f2ca, v220
	v_min_f32_e32 v221, 0x7149f2ca, v221
	v_min_f32_e32 v222, 0x7149f2ca, v222
	v_min_f32_e32 v223, 0x7149f2ca, v223
	v_min_f32_e32 v224, 0x7149f2ca, v224
	v_min_f32_e32 v225, 0x7149f2ca, v225
	v_min_f32_e32 v226, 0x7149f2ca, v226
	v_min_f32_e32 v227, 0x7149f2ca, v227
	v_min_f32_e32 v228, 0x7149f2ca, v228
	v_min_f32_e32 v229, 0x7149f2ca, v229
	v_add_f32_e32 v214, 1.0, v214
	v_add_f32_e32 v215, 1.0, v215
	v_add_f32_e32 v216, 1.0, v216
	v_add_f32_e32 v217, 1.0, v217
	v_add_f32_e32 v218, 1.0, v218
	v_add_f32_e32 v219, 1.0, v219
	v_add_f32_e32 v220, 1.0, v220
	v_add_f32_e32 v221, 1.0, v221
	v_add_f32_e32 v222, 1.0, v222
	v_add_f32_e32 v223, 1.0, v223
	v_add_f32_e32 v224, 1.0, v224
	v_add_f32_e32 v225, 1.0, v225
	v_add_f32_e32 v226, 1.0, v226
	v_add_f32_e32 v227, 1.0, v227
	v_add_f32_e32 v228, 1.0, v228
	v_add_f32_e32 v229, 1.0, v229
	v_rcp_f32_e32 v214, v214
	v_rcp_f32_e32 v215, v215
	v_rcp_f32_e32 v216, v216
	v_rcp_f32_e32 v217, v217
	v_rcp_f32_e32 v218, v218
	v_rcp_f32_e32 v219, v219
	v_rcp_f32_e32 v220, v220
	v_rcp_f32_e32 v221, v221
	v_rcp_f32_e32 v222, v222
	v_rcp_f32_e32 v223, v223
	v_rcp_f32_e32 v224, v224
	v_rcp_f32_e32 v225, v225
	v_rcp_f32_e32 v226, v226
	v_rcp_f32_e32 v227, v227
	v_rcp_f32_e32 v228, v228
	v_rcp_f32_e32 v229, v229
	v_mov_b32_e32 v176, v172
	v_mul_f32_e32 v128, v128, v214
	v_mul_f32_e32 v129, v129, v215
	v_mul_f32_e32 v130, v130, v216
	v_mul_f32_e32 v131, v131, v217
	v_mul_f32_e32 v124, v124, v218
	v_mul_f32_e32 v125, v125, v219
	v_mul_f32_e32 v126, v126, v220
	v_mul_f32_e32 v127, v127, v221
	v_mul_f32_e32 v120, v120, v222
	v_mul_f32_e32 v121, v121, v223
	v_mul_f32_e32 v122, v122, v224
	v_mul_f32_e32 v123, v123, v225
	v_mul_f32_e32 v116, v116, v226
	v_mul_f32_e32 v117, v117, v227
	v_mul_f32_e32 v118, v118, v228
	v_mul_f32_e32 v119, v119, v229
	v_cvt_pk_bf16_f32 v128, v128, v129
	v_cvt_pk_bf16_f32 v129, v130, v131
	v_cvt_pk_bf16_f32 v124, v124, v125
	v_cvt_pk_bf16_f32 v125, v126, v127
	v_cvt_pk_bf16_f32 v120, v120, v121
	v_cvt_pk_bf16_f32 v121, v122, v123
	v_cvt_pk_bf16_f32 v116, v116, v117
	v_cvt_pk_bf16_f32 v117, v118, v119
	global_store_dwordx2 v176, v[128:129], s[2:3]
	global_store_dwordx2 v176, v[124:125], s[2:3] offset:32
	global_store_dwordx2 v176, v[120:121], s[2:3] offset:256
	global_store_dwordx2 v176, v[116:117], s[2:3] offset:288
	s_waitcnt vmcnt(8) lgkmcnt(0)
	v_lshlrev_b32_e32 v214, 16, v206
	v_and_b32_e32 v215, 0xffff0000, v206
	v_lshlrev_b32_e32 v216, 16, v207
	v_and_b32_e32 v217, 0xffff0000, v207
	v_lshlrev_b32_e32 v218, 16, v208
	v_and_b32_e32 v219, 0xffff0000, v208
	v_lshlrev_b32_e32 v220, 16, v209
	v_and_b32_e32 v221, 0xffff0000, v209
	v_lshlrev_b32_e32 v222, 16, v210
	v_and_b32_e32 v223, 0xffff0000, v210
	v_lshlrev_b32_e32 v224, 16, v211
	v_and_b32_e32 v225, 0xffff0000, v211
	v_lshlrev_b32_e32 v226, 16, v212
	v_and_b32_e32 v227, 0xffff0000, v212
	v_lshlrev_b32_e32 v228, 16, v213
	v_and_b32_e32 v229, 0xffff0000, v213
	v_add_u32_e32 v173, 0x72c00, v171
	global_load_dwordx2 v[206:207], v173, s[8:9]
	global_load_dwordx2 v[208:209], v173, s[8:9] offset:32
	global_load_dwordx2 v[210:211], v173, s[8:9] offset:256
	global_load_dwordx2 v[212:213], v173, s[8:9] offset:288
	ds_bpermute_b32 v96, v170, v96
	ds_bpermute_b32 v97, v170, v97
	ds_bpermute_b32 v98, v170, v98
	ds_bpermute_b32 v99, v170, v99
	ds_bpermute_b32 v92, v170, v92
	ds_bpermute_b32 v93, v170, v93
	ds_bpermute_b32 v94, v170, v94
	ds_bpermute_b32 v95, v170, v95
	ds_bpermute_b32 v88, v170, v88
	ds_bpermute_b32 v89, v170, v89
	ds_bpermute_b32 v90, v170, v90
	ds_bpermute_b32 v91, v170, v91
	ds_bpermute_b32 v84, v170, v84
	ds_bpermute_b32 v85, v170, v85
	ds_bpermute_b32 v86, v170, v86
	ds_bpermute_b32 v87, v170, v87
	v_mul_f32_e32 v214, 0xbfb8aa3b, v214
	v_mul_f32_e32 v215, 0xbfb8aa3b, v215
	v_mul_f32_e32 v216, 0xbfb8aa3b, v216
	v_mul_f32_e32 v217, 0xbfb8aa3b, v217
	v_mul_f32_e32 v218, 0xbfb8aa3b, v218
	v_mul_f32_e32 v219, 0xbfb8aa3b, v219
	v_mul_f32_e32 v220, 0xbfb8aa3b, v220
	v_mul_f32_e32 v221, 0xbfb8aa3b, v221
	v_mul_f32_e32 v222, 0xbfb8aa3b, v222
	v_mul_f32_e32 v223, 0xbfb8aa3b, v223
	v_mul_f32_e32 v224, 0xbfb8aa3b, v224
	v_mul_f32_e32 v225, 0xbfb8aa3b, v225
	v_mul_f32_e32 v226, 0xbfb8aa3b, v226
	v_mul_f32_e32 v227, 0xbfb8aa3b, v227
	v_mul_f32_e32 v228, 0xbfb8aa3b, v228
	v_mul_f32_e32 v229, 0xbfb8aa3b, v229
	v_exp_f32_e32 v214, v214
	v_exp_f32_e32 v215, v215
	v_exp_f32_e32 v216, v216
	v_exp_f32_e32 v217, v217
	v_exp_f32_e32 v218, v218
	v_exp_f32_e32 v219, v219
	v_exp_f32_e32 v220, v220
	v_exp_f32_e32 v221, v221
	v_exp_f32_e32 v222, v222
	v_exp_f32_e32 v223, v223
	v_exp_f32_e32 v224, v224
	v_exp_f32_e32 v225, v225
	v_exp_f32_e32 v226, v226
	v_exp_f32_e32 v227, v227
	v_exp_f32_e32 v228, v228
	v_exp_f32_e32 v229, v229
	v_min_f32_e32 v214, 0x7149f2ca, v214
	v_min_f32_e32 v215, 0x7149f2ca, v215
	v_min_f32_e32 v216, 0x7149f2ca, v216
	v_min_f32_e32 v217, 0x7149f2ca, v217
	v_min_f32_e32 v218, 0x7149f2ca, v218
	v_min_f32_e32 v219, 0x7149f2ca, v219
	v_min_f32_e32 v220, 0x7149f2ca, v220
	v_min_f32_e32 v221, 0x7149f2ca, v221
	v_min_f32_e32 v222, 0x7149f2ca, v222
	v_min_f32_e32 v223, 0x7149f2ca, v223
	v_min_f32_e32 v224, 0x7149f2ca, v224
	v_min_f32_e32 v225, 0x7149f2ca, v225
	v_min_f32_e32 v226, 0x7149f2ca, v226
	v_min_f32_e32 v227, 0x7149f2ca, v227
	v_min_f32_e32 v228, 0x7149f2ca, v228
	v_min_f32_e32 v229, 0x7149f2ca, v229
	v_add_f32_e32 v214, 1.0, v214
	v_add_f32_e32 v215, 1.0, v215
	v_add_f32_e32 v216, 1.0, v216
	v_add_f32_e32 v217, 1.0, v217
	v_add_f32_e32 v218, 1.0, v218
	v_add_f32_e32 v219, 1.0, v219
	v_add_f32_e32 v220, 1.0, v220
	v_add_f32_e32 v221, 1.0, v221
	v_add_f32_e32 v222, 1.0, v222
	v_add_f32_e32 v223, 1.0, v223
	v_add_f32_e32 v224, 1.0, v224
	v_add_f32_e32 v225, 1.0, v225
	v_add_f32_e32 v226, 1.0, v226
	v_add_f32_e32 v227, 1.0, v227
	v_add_f32_e32 v228, 1.0, v228
	v_add_f32_e32 v229, 1.0, v229
	v_rcp_f32_e32 v214, v214
	v_rcp_f32_e32 v215, v215
	v_rcp_f32_e32 v216, v216
	v_rcp_f32_e32 v217, v217
	v_rcp_f32_e32 v218, v218
	v_rcp_f32_e32 v219, v219
	v_rcp_f32_e32 v220, v220
	v_rcp_f32_e32 v221, v221
	v_rcp_f32_e32 v222, v222
	v_rcp_f32_e32 v223, v223
	v_rcp_f32_e32 v224, v224
	v_rcp_f32_e32 v225, v225
	v_rcp_f32_e32 v226, v226
	v_rcp_f32_e32 v227, v227
	v_rcp_f32_e32 v228, v228
	v_rcp_f32_e32 v229, v229
	v_add_u32_e32 v176, 0x8000, v172
	v_mul_f32_e32 v112, v112, v214
	v_mul_f32_e32 v113, v113, v215
	v_mul_f32_e32 v114, v114, v216
	v_mul_f32_e32 v115, v115, v217
	v_mul_f32_e32 v108, v108, v218
	v_mul_f32_e32 v109, v109, v219
	v_mul_f32_e32 v110, v110, v220
	v_mul_f32_e32 v111, v111, v221
	v_mul_f32_e32 v104, v104, v222
	v_mul_f32_e32 v105, v105, v223
	v_mul_f32_e32 v106, v106, v224
	v_mul_f32_e32 v107, v107, v225
	v_mul_f32_e32 v100, v100, v226
	v_mul_f32_e32 v101, v101, v227
	v_mul_f32_e32 v102, v102, v228
	v_mul_f32_e32 v103, v103, v229
	v_cvt_pk_bf16_f32 v112, v112, v113
	v_cvt_pk_bf16_f32 v113, v114, v115
	v_cvt_pk_bf16_f32 v108, v108, v109
	v_cvt_pk_bf16_f32 v109, v110, v111
	v_cvt_pk_bf16_f32 v104, v104, v105
	v_cvt_pk_bf16_f32 v105, v106, v107
	v_cvt_pk_bf16_f32 v100, v100, v101
	v_cvt_pk_bf16_f32 v101, v102, v103
	global_store_dwordx2 v176, v[112:113], s[2:3]
	global_store_dwordx2 v176, v[108:109], s[2:3] offset:32
	global_store_dwordx2 v176, v[104:105], s[2:3] offset:256
	global_store_dwordx2 v176, v[100:101], s[2:3] offset:288
	s_waitcnt vmcnt(12) lgkmcnt(0)
	v_lshlrev_b32_e32 v214, 16, v198
	v_and_b32_e32 v215, 0xffff0000, v198
	v_lshlrev_b32_e32 v216, 16, v199
	v_and_b32_e32 v217, 0xffff0000, v199
	v_lshlrev_b32_e32 v218, 16, v200
	v_and_b32_e32 v219, 0xffff0000, v200
	v_lshlrev_b32_e32 v220, 16, v201
	v_and_b32_e32 v221, 0xffff0000, v201
	v_lshlrev_b32_e32 v222, 16, v202
	v_and_b32_e32 v223, 0xffff0000, v202
	v_lshlrev_b32_e32 v224, 16, v203
	v_and_b32_e32 v225, 0xffff0000, v203
	v_lshlrev_b32_e32 v226, 16, v204
	v_and_b32_e32 v227, 0xffff0000, v204
	v_lshlrev_b32_e32 v228, 16, v205
	v_and_b32_e32 v229, 0xffff0000, v205
	v_add_u32_e32 v174, 0x132000, v171
	global_load_dwordx2 v[198:199], v174, s[8:9]
	global_load_dwordx2 v[200:201], v174, s[8:9] offset:32
	global_load_dwordx2 v[202:203], v174, s[8:9] offset:256
	global_load_dwordx2 v[204:205], v174, s[8:9] offset:288
	ds_bpermute_b32 v80, v170, v80
	ds_bpermute_b32 v81, v170, v81
	ds_bpermute_b32 v82, v170, v82
	ds_bpermute_b32 v83, v170, v83
	ds_bpermute_b32 v76, v170, v76
	ds_bpermute_b32 v77, v170, v77
	ds_bpermute_b32 v78, v170, v78
	ds_bpermute_b32 v79, v170, v79
	ds_bpermute_b32 v72, v170, v72
	ds_bpermute_b32 v73, v170, v73
	ds_bpermute_b32 v74, v170, v74
	ds_bpermute_b32 v75, v170, v75
	ds_bpermute_b32 v68, v170, v68
	ds_bpermute_b32 v69, v170, v69
	ds_bpermute_b32 v70, v170, v70
	ds_bpermute_b32 v71, v170, v71
	v_mul_f32_e32 v214, 0xbfb8aa3b, v214
	v_mul_f32_e32 v215, 0xbfb8aa3b, v215
	v_mul_f32_e32 v216, 0xbfb8aa3b, v216
	v_mul_f32_e32 v217, 0xbfb8aa3b, v217
	v_mul_f32_e32 v218, 0xbfb8aa3b, v218
	v_mul_f32_e32 v219, 0xbfb8aa3b, v219
	v_mul_f32_e32 v220, 0xbfb8aa3b, v220
	v_mul_f32_e32 v221, 0xbfb8aa3b, v221
	v_mul_f32_e32 v222, 0xbfb8aa3b, v222
	v_mul_f32_e32 v223, 0xbfb8aa3b, v223
	v_mul_f32_e32 v224, 0xbfb8aa3b, v224
	v_mul_f32_e32 v225, 0xbfb8aa3b, v225
	v_mul_f32_e32 v226, 0xbfb8aa3b, v226
	v_mul_f32_e32 v227, 0xbfb8aa3b, v227
	v_mul_f32_e32 v228, 0xbfb8aa3b, v228
	v_mul_f32_e32 v229, 0xbfb8aa3b, v229
	v_exp_f32_e32 v214, v214
	v_exp_f32_e32 v215, v215
	v_exp_f32_e32 v216, v216
	v_exp_f32_e32 v217, v217
	v_exp_f32_e32 v218, v218
	v_exp_f32_e32 v219, v219
	v_exp_f32_e32 v220, v220
	v_exp_f32_e32 v221, v221
	v_exp_f32_e32 v222, v222
	v_exp_f32_e32 v223, v223
	v_exp_f32_e32 v224, v224
	v_exp_f32_e32 v225, v225
	v_exp_f32_e32 v226, v226
	v_exp_f32_e32 v227, v227
	v_exp_f32_e32 v228, v228
	v_exp_f32_e32 v229, v229
	v_min_f32_e32 v214, 0x7149f2ca, v214
	v_min_f32_e32 v215, 0x7149f2ca, v215
	v_min_f32_e32 v216, 0x7149f2ca, v216
	v_min_f32_e32 v217, 0x7149f2ca, v217
	v_min_f32_e32 v218, 0x7149f2ca, v218
	v_min_f32_e32 v219, 0x7149f2ca, v219
	v_min_f32_e32 v220, 0x7149f2ca, v220
	v_min_f32_e32 v221, 0x7149f2ca, v221
	v_min_f32_e32 v222, 0x7149f2ca, v222
	v_min_f32_e32 v223, 0x7149f2ca, v223
	v_min_f32_e32 v224, 0x7149f2ca, v224
	v_min_f32_e32 v225, 0x7149f2ca, v225
	v_min_f32_e32 v226, 0x7149f2ca, v226
	v_min_f32_e32 v227, 0x7149f2ca, v227
	v_min_f32_e32 v228, 0x7149f2ca, v228
	v_min_f32_e32 v229, 0x7149f2ca, v229
	v_add_f32_e32 v214, 1.0, v214
	v_add_f32_e32 v215, 1.0, v215
	v_add_f32_e32 v216, 1.0, v216
	v_add_f32_e32 v217, 1.0, v217
	v_add_f32_e32 v218, 1.0, v218
	v_add_f32_e32 v219, 1.0, v219
	v_add_f32_e32 v220, 1.0, v220
	v_add_f32_e32 v221, 1.0, v221
	v_add_f32_e32 v222, 1.0, v222
	v_add_f32_e32 v223, 1.0, v223
	v_add_f32_e32 v224, 1.0, v224
	v_add_f32_e32 v225, 1.0, v225
	v_add_f32_e32 v226, 1.0, v226
	v_add_f32_e32 v227, 1.0, v227
	v_add_f32_e32 v228, 1.0, v228
	v_add_f32_e32 v229, 1.0, v229
	v_rcp_f32_e32 v214, v214
	v_rcp_f32_e32 v215, v215
	v_rcp_f32_e32 v216, v216
	v_rcp_f32_e32 v217, v217
	v_rcp_f32_e32 v218, v218
	v_rcp_f32_e32 v219, v219
	v_rcp_f32_e32 v220, v220
	v_rcp_f32_e32 v221, v221
	v_rcp_f32_e32 v222, v222
	v_rcp_f32_e32 v223, v223
	v_rcp_f32_e32 v224, v224
	v_rcp_f32_e32 v225, v225
	v_rcp_f32_e32 v226, v226
	v_rcp_f32_e32 v227, v227
	v_rcp_f32_e32 v228, v228
	v_rcp_f32_e32 v229, v229
	v_add_u32_e32 v176, 0x10000, v172
	v_mul_f32_e32 v96, v96, v214
	v_mul_f32_e32 v97, v97, v215
	v_mul_f32_e32 v98, v98, v216
	v_mul_f32_e32 v99, v99, v217
	v_mul_f32_e32 v92, v92, v218
	v_mul_f32_e32 v93, v93, v219
	v_mul_f32_e32 v94, v94, v220
	v_mul_f32_e32 v95, v95, v221
	v_mul_f32_e32 v88, v88, v222
	v_mul_f32_e32 v89, v89, v223
	v_mul_f32_e32 v90, v90, v224
	v_mul_f32_e32 v91, v91, v225
	v_mul_f32_e32 v84, v84, v226
	v_mul_f32_e32 v85, v85, v227
	v_mul_f32_e32 v86, v86, v228
	v_mul_f32_e32 v87, v87, v229
	v_cvt_pk_bf16_f32 v96, v96, v97
	v_cvt_pk_bf16_f32 v97, v98, v99
	v_cvt_pk_bf16_f32 v92, v92, v93
	v_cvt_pk_bf16_f32 v93, v94, v95
	v_cvt_pk_bf16_f32 v88, v88, v89
	v_cvt_pk_bf16_f32 v89, v90, v91
	v_cvt_pk_bf16_f32 v84, v84, v85
	v_cvt_pk_bf16_f32 v85, v86, v87
	global_store_dwordx2 v176, v[96:97], s[2:3]
	global_store_dwordx2 v176, v[92:93], s[2:3] offset:32
	global_store_dwordx2 v176, v[88:89], s[2:3] offset:256
	global_store_dwordx2 v176, v[84:85], s[2:3] offset:288
	s_waitcnt vmcnt(12) lgkmcnt(0)
	v_lshlrev_b32_e32 v214, 16, v206
	v_and_b32_e32 v215, 0xffff0000, v206
	v_lshlrev_b32_e32 v216, 16, v207
	v_and_b32_e32 v217, 0xffff0000, v207
	v_lshlrev_b32_e32 v218, 16, v208
	v_and_b32_e32 v219, 0xffff0000, v208
	v_lshlrev_b32_e32 v220, 16, v209
	v_and_b32_e32 v221, 0xffff0000, v209
	v_lshlrev_b32_e32 v222, 16, v210
	v_and_b32_e32 v223, 0xffff0000, v210
	v_lshlrev_b32_e32 v224, 16, v211
	v_and_b32_e32 v225, 0xffff0000, v211
	v_lshlrev_b32_e32 v226, 16, v212
	v_and_b32_e32 v227, 0xffff0000, v212
	v_lshlrev_b32_e32 v228, 16, v213
	v_and_b32_e32 v229, 0xffff0000, v213
	v_add_u32_e32 v175, 0x158400, v171
	global_load_dwordx2 v[206:207], v175, s[8:9]
	global_load_dwordx2 v[208:209], v175, s[8:9] offset:32
	global_load_dwordx2 v[210:211], v175, s[8:9] offset:256
	global_load_dwordx2 v[212:213], v175, s[8:9] offset:288
	ds_bpermute_b32 v64, v170, v64
	ds_bpermute_b32 v65, v170, v65
	ds_bpermute_b32 v66, v170, v66
	ds_bpermute_b32 v67, v170, v67
	ds_bpermute_b32 v60, v170, v60
	ds_bpermute_b32 v61, v170, v61
	ds_bpermute_b32 v62, v170, v62
	ds_bpermute_b32 v63, v170, v63
	ds_bpermute_b32 v56, v170, v56
	ds_bpermute_b32 v57, v170, v57
	ds_bpermute_b32 v58, v170, v58
	ds_bpermute_b32 v59, v170, v59
	ds_bpermute_b32 v52, v170, v52
	ds_bpermute_b32 v53, v170, v53
	ds_bpermute_b32 v54, v170, v54
	ds_bpermute_b32 v55, v170, v55
	v_mul_f32_e32 v214, 0xbfb8aa3b, v214
	v_mul_f32_e32 v215, 0xbfb8aa3b, v215
	v_mul_f32_e32 v216, 0xbfb8aa3b, v216
	v_mul_f32_e32 v217, 0xbfb8aa3b, v217
	v_mul_f32_e32 v218, 0xbfb8aa3b, v218
	v_mul_f32_e32 v219, 0xbfb8aa3b, v219
	v_mul_f32_e32 v220, 0xbfb8aa3b, v220
	v_mul_f32_e32 v221, 0xbfb8aa3b, v221
	v_mul_f32_e32 v222, 0xbfb8aa3b, v222
	v_mul_f32_e32 v223, 0xbfb8aa3b, v223
	v_mul_f32_e32 v224, 0xbfb8aa3b, v224
	v_mul_f32_e32 v225, 0xbfb8aa3b, v225
	v_mul_f32_e32 v226, 0xbfb8aa3b, v226
	v_mul_f32_e32 v227, 0xbfb8aa3b, v227
	v_mul_f32_e32 v228, 0xbfb8aa3b, v228
	v_mul_f32_e32 v229, 0xbfb8aa3b, v229
	v_exp_f32_e32 v214, v214
	v_exp_f32_e32 v215, v215
	v_exp_f32_e32 v216, v216
	v_exp_f32_e32 v217, v217
	v_exp_f32_e32 v218, v218
	v_exp_f32_e32 v219, v219
	v_exp_f32_e32 v220, v220
	v_exp_f32_e32 v221, v221
	v_exp_f32_e32 v222, v222
	v_exp_f32_e32 v223, v223
	v_exp_f32_e32 v224, v224
	v_exp_f32_e32 v225, v225
	v_exp_f32_e32 v226, v226
	v_exp_f32_e32 v227, v227
	v_exp_f32_e32 v228, v228
	v_exp_f32_e32 v229, v229
	v_min_f32_e32 v214, 0x7149f2ca, v214
	v_min_f32_e32 v215, 0x7149f2ca, v215
	v_min_f32_e32 v216, 0x7149f2ca, v216
	v_min_f32_e32 v217, 0x7149f2ca, v217
	v_min_f32_e32 v218, 0x7149f2ca, v218
	v_min_f32_e32 v219, 0x7149f2ca, v219
	v_min_f32_e32 v220, 0x7149f2ca, v220
	v_min_f32_e32 v221, 0x7149f2ca, v221
	v_min_f32_e32 v222, 0x7149f2ca, v222
	v_min_f32_e32 v223, 0x7149f2ca, v223
	v_min_f32_e32 v224, 0x7149f2ca, v224
	v_min_f32_e32 v225, 0x7149f2ca, v225
	v_min_f32_e32 v226, 0x7149f2ca, v226
	v_min_f32_e32 v227, 0x7149f2ca, v227
	v_min_f32_e32 v228, 0x7149f2ca, v228
	v_min_f32_e32 v229, 0x7149f2ca, v229
	v_add_f32_e32 v214, 1.0, v214
	v_add_f32_e32 v215, 1.0, v215
	v_add_f32_e32 v216, 1.0, v216
	v_add_f32_e32 v217, 1.0, v217
	v_add_f32_e32 v218, 1.0, v218
	v_add_f32_e32 v219, 1.0, v219
	v_add_f32_e32 v220, 1.0, v220
	v_add_f32_e32 v221, 1.0, v221
	v_add_f32_e32 v222, 1.0, v222
	v_add_f32_e32 v223, 1.0, v223
	v_add_f32_e32 v224, 1.0, v224
	v_add_f32_e32 v225, 1.0, v225
	v_add_f32_e32 v226, 1.0, v226
	v_add_f32_e32 v227, 1.0, v227
	v_add_f32_e32 v228, 1.0, v228
	v_add_f32_e32 v229, 1.0, v229
	v_rcp_f32_e32 v214, v214
	v_rcp_f32_e32 v215, v215
	v_rcp_f32_e32 v216, v216
	v_rcp_f32_e32 v217, v217
	v_rcp_f32_e32 v218, v218
	v_rcp_f32_e32 v219, v219
	v_rcp_f32_e32 v220, v220
	v_rcp_f32_e32 v221, v221
	v_rcp_f32_e32 v222, v222
	v_rcp_f32_e32 v223, v223
	v_rcp_f32_e32 v224, v224
	v_rcp_f32_e32 v225, v225
	v_rcp_f32_e32 v226, v226
	v_rcp_f32_e32 v227, v227
	v_rcp_f32_e32 v228, v228
	v_rcp_f32_e32 v229, v229
	v_add_u32_e32 v176, 0x18000, v172
	v_mul_f32_e32 v80, v80, v214
	v_mul_f32_e32 v81, v81, v215
	v_mul_f32_e32 v82, v82, v216
	v_mul_f32_e32 v83, v83, v217
	v_mul_f32_e32 v76, v76, v218
	v_mul_f32_e32 v77, v77, v219
	v_mul_f32_e32 v78, v78, v220
	v_mul_f32_e32 v79, v79, v221
	v_mul_f32_e32 v72, v72, v222
	v_mul_f32_e32 v73, v73, v223
	v_mul_f32_e32 v74, v74, v224
	v_mul_f32_e32 v75, v75, v225
	v_mul_f32_e32 v68, v68, v226
	v_mul_f32_e32 v69, v69, v227
	v_mul_f32_e32 v70, v70, v228
	v_mul_f32_e32 v71, v71, v229
	v_cvt_pk_bf16_f32 v80, v80, v81
	v_cvt_pk_bf16_f32 v81, v82, v83
	v_cvt_pk_bf16_f32 v76, v76, v77
	v_cvt_pk_bf16_f32 v77, v78, v79
	v_cvt_pk_bf16_f32 v72, v72, v73
	v_cvt_pk_bf16_f32 v73, v74, v75
	v_cvt_pk_bf16_f32 v68, v68, v69
	v_cvt_pk_bf16_f32 v69, v70, v71
	global_store_dwordx2 v176, v[80:81], s[2:3]
	global_store_dwordx2 v176, v[76:77], s[2:3] offset:32
	global_store_dwordx2 v176, v[72:73], s[2:3] offset:256
	global_store_dwordx2 v176, v[68:69], s[2:3] offset:288
	s_waitcnt vmcnt(12) lgkmcnt(0)
	v_lshlrev_b32_e32 v214, 16, v198
	v_and_b32_e32 v215, 0xffff0000, v198
	v_lshlrev_b32_e32 v216, 16, v199
	v_and_b32_e32 v217, 0xffff0000, v199
	v_lshlrev_b32_e32 v218, 16, v200
	v_and_b32_e32 v219, 0xffff0000, v200
	v_lshlrev_b32_e32 v220, 16, v201
	v_and_b32_e32 v221, 0xffff0000, v201
	v_lshlrev_b32_e32 v222, 16, v202
	v_and_b32_e32 v223, 0xffff0000, v202
	v_lshlrev_b32_e32 v224, 16, v203
	v_and_b32_e32 v225, 0xffff0000, v203
	v_lshlrev_b32_e32 v226, 16, v204
	v_and_b32_e32 v227, 0xffff0000, v204
	v_lshlrev_b32_e32 v228, 16, v205
	v_and_b32_e32 v229, 0xffff0000, v205
	v_add_u32_e32 v173, 0x17e800, v171
	global_load_dwordx2 v[198:199], v173, s[8:9]
	global_load_dwordx2 v[200:201], v173, s[8:9] offset:32
	global_load_dwordx2 v[202:203], v173, s[8:9] offset:256
	global_load_dwordx2 v[204:205], v173, s[8:9] offset:288
	ds_bpermute_b32 v48, v170, v48
	ds_bpermute_b32 v49, v170, v49
	ds_bpermute_b32 v50, v170, v50
	ds_bpermute_b32 v51, v170, v51
	ds_bpermute_b32 v44, v170, v44
	ds_bpermute_b32 v45, v170, v45
	ds_bpermute_b32 v46, v170, v46
	ds_bpermute_b32 v47, v170, v47
	ds_bpermute_b32 v40, v170, v40
	ds_bpermute_b32 v41, v170, v41
	ds_bpermute_b32 v42, v170, v42
	ds_bpermute_b32 v43, v170, v43
	ds_bpermute_b32 v36, v170, v36
	ds_bpermute_b32 v37, v170, v37
	ds_bpermute_b32 v38, v170, v38
	ds_bpermute_b32 v39, v170, v39
	v_mul_f32_e32 v214, 0xbfb8aa3b, v214
	v_mul_f32_e32 v215, 0xbfb8aa3b, v215
	v_mul_f32_e32 v216, 0xbfb8aa3b, v216
	v_mul_f32_e32 v217, 0xbfb8aa3b, v217
	v_mul_f32_e32 v218, 0xbfb8aa3b, v218
	v_mul_f32_e32 v219, 0xbfb8aa3b, v219
	v_mul_f32_e32 v220, 0xbfb8aa3b, v220
	v_mul_f32_e32 v221, 0xbfb8aa3b, v221
	v_mul_f32_e32 v222, 0xbfb8aa3b, v222
	v_mul_f32_e32 v223, 0xbfb8aa3b, v223
	v_mul_f32_e32 v224, 0xbfb8aa3b, v224
	v_mul_f32_e32 v225, 0xbfb8aa3b, v225
	v_mul_f32_e32 v226, 0xbfb8aa3b, v226
	v_mul_f32_e32 v227, 0xbfb8aa3b, v227
	v_mul_f32_e32 v228, 0xbfb8aa3b, v228
	v_mul_f32_e32 v229, 0xbfb8aa3b, v229
	v_exp_f32_e32 v214, v214
	v_exp_f32_e32 v215, v215
	v_exp_f32_e32 v216, v216
	v_exp_f32_e32 v217, v217
	v_exp_f32_e32 v218, v218
	v_exp_f32_e32 v219, v219
	v_exp_f32_e32 v220, v220
	v_exp_f32_e32 v221, v221
	v_exp_f32_e32 v222, v222
	v_exp_f32_e32 v223, v223
	v_exp_f32_e32 v224, v224
	v_exp_f32_e32 v225, v225
	v_exp_f32_e32 v226, v226
	v_exp_f32_e32 v227, v227
	v_exp_f32_e32 v228, v228
	v_exp_f32_e32 v229, v229
	v_min_f32_e32 v214, 0x7149f2ca, v214
	v_min_f32_e32 v215, 0x7149f2ca, v215
	v_min_f32_e32 v216, 0x7149f2ca, v216
	v_min_f32_e32 v217, 0x7149f2ca, v217
	v_min_f32_e32 v218, 0x7149f2ca, v218
	v_min_f32_e32 v219, 0x7149f2ca, v219
	v_min_f32_e32 v220, 0x7149f2ca, v220
	v_min_f32_e32 v221, 0x7149f2ca, v221
	v_min_f32_e32 v222, 0x7149f2ca, v222
	v_min_f32_e32 v223, 0x7149f2ca, v223
	v_min_f32_e32 v224, 0x7149f2ca, v224
	v_min_f32_e32 v225, 0x7149f2ca, v225
	v_min_f32_e32 v226, 0x7149f2ca, v226
	v_min_f32_e32 v227, 0x7149f2ca, v227
	v_min_f32_e32 v228, 0x7149f2ca, v228
	v_min_f32_e32 v229, 0x7149f2ca, v229
	v_add_f32_e32 v214, 1.0, v214
	v_add_f32_e32 v215, 1.0, v215
	v_add_f32_e32 v216, 1.0, v216
	v_add_f32_e32 v217, 1.0, v217
	v_add_f32_e32 v218, 1.0, v218
	v_add_f32_e32 v219, 1.0, v219
	v_add_f32_e32 v220, 1.0, v220
	v_add_f32_e32 v221, 1.0, v221
	v_add_f32_e32 v222, 1.0, v222
	v_add_f32_e32 v223, 1.0, v223
	v_add_f32_e32 v224, 1.0, v224
	v_add_f32_e32 v225, 1.0, v225
	v_add_f32_e32 v226, 1.0, v226
	v_add_f32_e32 v227, 1.0, v227
	v_add_f32_e32 v228, 1.0, v228
	v_add_f32_e32 v229, 1.0, v229
	v_rcp_f32_e32 v214, v214
	v_rcp_f32_e32 v215, v215
	v_rcp_f32_e32 v216, v216
	v_rcp_f32_e32 v217, v217
	v_rcp_f32_e32 v218, v218
	v_rcp_f32_e32 v219, v219
	v_rcp_f32_e32 v220, v220
	v_rcp_f32_e32 v221, v221
	v_rcp_f32_e32 v222, v222
	v_rcp_f32_e32 v223, v223
	v_rcp_f32_e32 v224, v224
	v_rcp_f32_e32 v225, v225
	v_rcp_f32_e32 v226, v226
	v_rcp_f32_e32 v227, v227
	v_rcp_f32_e32 v228, v228
	v_rcp_f32_e32 v229, v229
	v_add_u32_e32 v176, 0x40000, v172
	v_mul_f32_e32 v64, v64, v214
	v_mul_f32_e32 v65, v65, v215
	v_mul_f32_e32 v66, v66, v216
	v_mul_f32_e32 v67, v67, v217
	v_mul_f32_e32 v60, v60, v218
	v_mul_f32_e32 v61, v61, v219
	v_mul_f32_e32 v62, v62, v220
	v_mul_f32_e32 v63, v63, v221
	v_mul_f32_e32 v56, v56, v222
	v_mul_f32_e32 v57, v57, v223
	v_mul_f32_e32 v58, v58, v224
	v_mul_f32_e32 v59, v59, v225
	v_mul_f32_e32 v52, v52, v226
	v_mul_f32_e32 v53, v53, v227
	v_mul_f32_e32 v54, v54, v228
	v_mul_f32_e32 v55, v55, v229
	v_cvt_pk_bf16_f32 v64, v64, v65
	v_cvt_pk_bf16_f32 v65, v66, v67
	v_cvt_pk_bf16_f32 v60, v60, v61
	v_cvt_pk_bf16_f32 v61, v62, v63
	v_cvt_pk_bf16_f32 v56, v56, v57
	v_cvt_pk_bf16_f32 v57, v58, v59
	v_cvt_pk_bf16_f32 v52, v52, v53
	v_cvt_pk_bf16_f32 v53, v54, v55
	global_store_dwordx2 v176, v[64:65], s[2:3]
	global_store_dwordx2 v176, v[60:61], s[2:3] offset:32
	global_store_dwordx2 v176, v[56:57], s[2:3] offset:256
	global_store_dwordx2 v176, v[52:53], s[2:3] offset:288
	s_waitcnt vmcnt(12) lgkmcnt(0)
	v_lshlrev_b32_e32 v214, 16, v206
	v_and_b32_e32 v215, 0xffff0000, v206
	v_lshlrev_b32_e32 v216, 16, v207
	v_and_b32_e32 v217, 0xffff0000, v207
	v_lshlrev_b32_e32 v218, 16, v208
	v_and_b32_e32 v219, 0xffff0000, v208
	v_lshlrev_b32_e32 v220, 16, v209
	v_and_b32_e32 v221, 0xffff0000, v209
	v_lshlrev_b32_e32 v222, 16, v210
	v_and_b32_e32 v223, 0xffff0000, v210
	v_lshlrev_b32_e32 v224, 16, v211
	v_and_b32_e32 v225, 0xffff0000, v211
	v_lshlrev_b32_e32 v226, 16, v212
	v_and_b32_e32 v227, 0xffff0000, v212
	v_lshlrev_b32_e32 v228, 16, v213
	v_and_b32_e32 v229, 0xffff0000, v213
	v_add_u32_e32 v174, 0x1a4c00, v171
	global_load_dwordx2 v[206:207], v174, s[8:9]
	global_load_dwordx2 v[208:209], v174, s[8:9] offset:32
	global_load_dwordx2 v[210:211], v174, s[8:9] offset:256
	global_load_dwordx2 v[212:213], v174, s[8:9] offset:288
	ds_bpermute_b32 v32, v170, v32
	ds_bpermute_b32 v33, v170, v33
	ds_bpermute_b32 v34, v170, v34
	ds_bpermute_b32 v35, v170, v35
	ds_bpermute_b32 v28, v170, v28
	ds_bpermute_b32 v29, v170, v29
	ds_bpermute_b32 v30, v170, v30
	ds_bpermute_b32 v31, v170, v31
	ds_bpermute_b32 v24, v170, v24
	ds_bpermute_b32 v25, v170, v25
	ds_bpermute_b32 v26, v170, v26
	ds_bpermute_b32 v27, v170, v27
	ds_bpermute_b32 v20, v170, v20
	ds_bpermute_b32 v21, v170, v21
	ds_bpermute_b32 v22, v170, v22
	ds_bpermute_b32 v23, v170, v23
	v_mul_f32_e32 v214, 0xbfb8aa3b, v214
	v_mul_f32_e32 v215, 0xbfb8aa3b, v215
	v_mul_f32_e32 v216, 0xbfb8aa3b, v216
	v_mul_f32_e32 v217, 0xbfb8aa3b, v217
	v_mul_f32_e32 v218, 0xbfb8aa3b, v218
	v_mul_f32_e32 v219, 0xbfb8aa3b, v219
	v_mul_f32_e32 v220, 0xbfb8aa3b, v220
	v_mul_f32_e32 v221, 0xbfb8aa3b, v221
	v_mul_f32_e32 v222, 0xbfb8aa3b, v222
	v_mul_f32_e32 v223, 0xbfb8aa3b, v223
	v_mul_f32_e32 v224, 0xbfb8aa3b, v224
	v_mul_f32_e32 v225, 0xbfb8aa3b, v225
	v_mul_f32_e32 v226, 0xbfb8aa3b, v226
	v_mul_f32_e32 v227, 0xbfb8aa3b, v227
	v_mul_f32_e32 v228, 0xbfb8aa3b, v228
	v_mul_f32_e32 v229, 0xbfb8aa3b, v229
	v_exp_f32_e32 v214, v214
	v_exp_f32_e32 v215, v215
	v_exp_f32_e32 v216, v216
	v_exp_f32_e32 v217, v217
	v_exp_f32_e32 v218, v218
	v_exp_f32_e32 v219, v219
	v_exp_f32_e32 v220, v220
	v_exp_f32_e32 v221, v221
	v_exp_f32_e32 v222, v222
	v_exp_f32_e32 v223, v223
	v_exp_f32_e32 v224, v224
	v_exp_f32_e32 v225, v225
	v_exp_f32_e32 v226, v226
	v_exp_f32_e32 v227, v227
	v_exp_f32_e32 v228, v228
	v_exp_f32_e32 v229, v229
	v_min_f32_e32 v214, 0x7149f2ca, v214
	v_min_f32_e32 v215, 0x7149f2ca, v215
	v_min_f32_e32 v216, 0x7149f2ca, v216
	v_min_f32_e32 v217, 0x7149f2ca, v217
	v_min_f32_e32 v218, 0x7149f2ca, v218
	v_min_f32_e32 v219, 0x7149f2ca, v219
	v_min_f32_e32 v220, 0x7149f2ca, v220
	v_min_f32_e32 v221, 0x7149f2ca, v221
	v_min_f32_e32 v222, 0x7149f2ca, v222
	v_min_f32_e32 v223, 0x7149f2ca, v223
	v_min_f32_e32 v224, 0x7149f2ca, v224
	v_min_f32_e32 v225, 0x7149f2ca, v225
	v_min_f32_e32 v226, 0x7149f2ca, v226
	v_min_f32_e32 v227, 0x7149f2ca, v227
	v_min_f32_e32 v228, 0x7149f2ca, v228
	v_min_f32_e32 v229, 0x7149f2ca, v229
	v_add_f32_e32 v214, 1.0, v214
	v_add_f32_e32 v215, 1.0, v215
	v_add_f32_e32 v216, 1.0, v216
	v_add_f32_e32 v217, 1.0, v217
	v_add_f32_e32 v218, 1.0, v218
	v_add_f32_e32 v219, 1.0, v219
	v_add_f32_e32 v220, 1.0, v220
	v_add_f32_e32 v221, 1.0, v221
	v_add_f32_e32 v222, 1.0, v222
	v_add_f32_e32 v223, 1.0, v223
	v_add_f32_e32 v224, 1.0, v224
	v_add_f32_e32 v225, 1.0, v225
	v_add_f32_e32 v226, 1.0, v226
	v_add_f32_e32 v227, 1.0, v227
	v_add_f32_e32 v228, 1.0, v228
	v_add_f32_e32 v229, 1.0, v229
	v_rcp_f32_e32 v214, v214
	v_rcp_f32_e32 v215, v215
	v_rcp_f32_e32 v216, v216
	v_rcp_f32_e32 v217, v217
	v_rcp_f32_e32 v218, v218
	v_rcp_f32_e32 v219, v219
	v_rcp_f32_e32 v220, v220
	v_rcp_f32_e32 v221, v221
	v_rcp_f32_e32 v222, v222
	v_rcp_f32_e32 v223, v223
	v_rcp_f32_e32 v224, v224
	v_rcp_f32_e32 v225, v225
	v_rcp_f32_e32 v226, v226
	v_rcp_f32_e32 v227, v227
	v_rcp_f32_e32 v228, v228
	v_rcp_f32_e32 v229, v229
	v_add_u32_e32 v176, 0x48000, v172
	v_mul_f32_e32 v48, v48, v214
	v_mul_f32_e32 v49, v49, v215
	v_mul_f32_e32 v50, v50, v216
	v_mul_f32_e32 v51, v51, v217
	v_mul_f32_e32 v44, v44, v218
	v_mul_f32_e32 v45, v45, v219
	v_mul_f32_e32 v46, v46, v220
	v_mul_f32_e32 v47, v47, v221
	v_mul_f32_e32 v40, v40, v222
	v_mul_f32_e32 v41, v41, v223
	v_mul_f32_e32 v42, v42, v224
	v_mul_f32_e32 v43, v43, v225
	v_mul_f32_e32 v36, v36, v226
	v_mul_f32_e32 v37, v37, v227
	v_mul_f32_e32 v38, v38, v228
	v_mul_f32_e32 v39, v39, v229
	v_cvt_pk_bf16_f32 v48, v48, v49
	v_cvt_pk_bf16_f32 v49, v50, v51
	v_cvt_pk_bf16_f32 v44, v44, v45
	v_cvt_pk_bf16_f32 v45, v46, v47
	v_cvt_pk_bf16_f32 v40, v40, v41
	v_cvt_pk_bf16_f32 v41, v42, v43
	v_cvt_pk_bf16_f32 v36, v36, v37
	v_cvt_pk_bf16_f32 v37, v38, v39
	global_store_dwordx2 v176, v[48:49], s[2:3]
	global_store_dwordx2 v176, v[44:45], s[2:3] offset:32
	global_store_dwordx2 v176, v[40:41], s[2:3] offset:256
	global_store_dwordx2 v176, v[36:37], s[2:3] offset:288
	s_waitcnt vmcnt(12) lgkmcnt(0)
	v_lshlrev_b32_e32 v214, 16, v198
	v_and_b32_e32 v215, 0xffff0000, v198
	v_lshlrev_b32_e32 v216, 16, v199
	v_and_b32_e32 v217, 0xffff0000, v199
	v_lshlrev_b32_e32 v218, 16, v200
	v_and_b32_e32 v219, 0xffff0000, v200
	v_lshlrev_b32_e32 v220, 16, v201
	v_and_b32_e32 v221, 0xffff0000, v201
	v_lshlrev_b32_e32 v222, 16, v202
	v_and_b32_e32 v223, 0xffff0000, v202
	v_lshlrev_b32_e32 v224, 16, v203
	v_and_b32_e32 v225, 0xffff0000, v203
	v_lshlrev_b32_e32 v226, 16, v204
	v_and_b32_e32 v227, 0xffff0000, v204
	v_lshlrev_b32_e32 v228, 16, v205
	v_and_b32_e32 v229, 0xffff0000, v205
	ds_bpermute_b32 v16, v170, v16
	ds_bpermute_b32 v17, v170, v17
	ds_bpermute_b32 v18, v170, v18
	ds_bpermute_b32 v19, v170, v19
	ds_bpermute_b32 v12, v170, v12
	ds_bpermute_b32 v13, v170, v13
	ds_bpermute_b32 v14, v170, v14
	ds_bpermute_b32 v15, v170, v15
	ds_bpermute_b32 v8, v170, v8
	ds_bpermute_b32 v9, v170, v9
	ds_bpermute_b32 v10, v170, v10
	ds_bpermute_b32 v11, v170, v11
	ds_bpermute_b32 v4, v170, v4
	ds_bpermute_b32 v5, v170, v5
	ds_bpermute_b32 v6, v170, v6
	ds_bpermute_b32 v7, v170, v7
	v_mul_f32_e32 v214, 0xbfb8aa3b, v214
	v_mul_f32_e32 v215, 0xbfb8aa3b, v215
	v_mul_f32_e32 v216, 0xbfb8aa3b, v216
	v_mul_f32_e32 v217, 0xbfb8aa3b, v217
	v_mul_f32_e32 v218, 0xbfb8aa3b, v218
	v_mul_f32_e32 v219, 0xbfb8aa3b, v219
	v_mul_f32_e32 v220, 0xbfb8aa3b, v220
	v_mul_f32_e32 v221, 0xbfb8aa3b, v221
	v_mul_f32_e32 v222, 0xbfb8aa3b, v222
	v_mul_f32_e32 v223, 0xbfb8aa3b, v223
	v_mul_f32_e32 v224, 0xbfb8aa3b, v224
	v_mul_f32_e32 v225, 0xbfb8aa3b, v225
	v_mul_f32_e32 v226, 0xbfb8aa3b, v226
	v_mul_f32_e32 v227, 0xbfb8aa3b, v227
	v_mul_f32_e32 v228, 0xbfb8aa3b, v228
	v_mul_f32_e32 v229, 0xbfb8aa3b, v229
	v_exp_f32_e32 v214, v214
	v_exp_f32_e32 v215, v215
	v_exp_f32_e32 v216, v216
	v_exp_f32_e32 v217, v217
	v_exp_f32_e32 v218, v218
	v_exp_f32_e32 v219, v219
	v_exp_f32_e32 v220, v220
	v_exp_f32_e32 v221, v221
	v_exp_f32_e32 v222, v222
	v_exp_f32_e32 v223, v223
	v_exp_f32_e32 v224, v224
	v_exp_f32_e32 v225, v225
	v_exp_f32_e32 v226, v226
	v_exp_f32_e32 v227, v227
	v_exp_f32_e32 v228, v228
	v_exp_f32_e32 v229, v229
	v_min_f32_e32 v214, 0x7149f2ca, v214
	v_min_f32_e32 v215, 0x7149f2ca, v215
	v_min_f32_e32 v216, 0x7149f2ca, v216
	v_min_f32_e32 v217, 0x7149f2ca, v217
	v_min_f32_e32 v218, 0x7149f2ca, v218
	v_min_f32_e32 v219, 0x7149f2ca, v219
	v_min_f32_e32 v220, 0x7149f2ca, v220
	v_min_f32_e32 v221, 0x7149f2ca, v221
	v_min_f32_e32 v222, 0x7149f2ca, v222
	v_min_f32_e32 v223, 0x7149f2ca, v223
	v_min_f32_e32 v224, 0x7149f2ca, v224
	v_min_f32_e32 v225, 0x7149f2ca, v225
	v_min_f32_e32 v226, 0x7149f2ca, v226
	v_min_f32_e32 v227, 0x7149f2ca, v227
	v_min_f32_e32 v228, 0x7149f2ca, v228
	v_min_f32_e32 v229, 0x7149f2ca, v229
	v_add_f32_e32 v214, 1.0, v214
	v_add_f32_e32 v215, 1.0, v215
	v_add_f32_e32 v216, 1.0, v216
	v_add_f32_e32 v217, 1.0, v217
	v_add_f32_e32 v218, 1.0, v218
	v_add_f32_e32 v219, 1.0, v219
	v_add_f32_e32 v220, 1.0, v220
	v_add_f32_e32 v221, 1.0, v221
	v_add_f32_e32 v222, 1.0, v222
	v_add_f32_e32 v223, 1.0, v223
	v_add_f32_e32 v224, 1.0, v224
	v_add_f32_e32 v225, 1.0, v225
	v_add_f32_e32 v226, 1.0, v226
	v_add_f32_e32 v227, 1.0, v227
	v_add_f32_e32 v228, 1.0, v228
	v_add_f32_e32 v229, 1.0, v229
	v_rcp_f32_e32 v214, v214
	v_rcp_f32_e32 v215, v215
	v_rcp_f32_e32 v216, v216
	v_rcp_f32_e32 v217, v217
	v_rcp_f32_e32 v218, v218
	v_rcp_f32_e32 v219, v219
	v_rcp_f32_e32 v220, v220
	v_rcp_f32_e32 v221, v221
	v_rcp_f32_e32 v222, v222
	v_rcp_f32_e32 v223, v223
	v_rcp_f32_e32 v224, v224
	v_rcp_f32_e32 v225, v225
	v_rcp_f32_e32 v226, v226
	v_rcp_f32_e32 v227, v227
	v_rcp_f32_e32 v228, v228
	v_rcp_f32_e32 v229, v229
	v_add_u32_e32 v176, 0x50000, v172
	v_mul_f32_e32 v32, v32, v214
	v_mul_f32_e32 v33, v33, v215
	v_mul_f32_e32 v34, v34, v216
	v_mul_f32_e32 v35, v35, v217
	v_mul_f32_e32 v28, v28, v218
	v_mul_f32_e32 v29, v29, v219
	v_mul_f32_e32 v30, v30, v220
	v_mul_f32_e32 v31, v31, v221
	v_mul_f32_e32 v24, v24, v222
	v_mul_f32_e32 v25, v25, v223
	v_mul_f32_e32 v26, v26, v224
	v_mul_f32_e32 v27, v27, v225
	v_mul_f32_e32 v20, v20, v226
	v_mul_f32_e32 v21, v21, v227
	v_mul_f32_e32 v22, v22, v228
	v_mul_f32_e32 v23, v23, v229
	v_cvt_pk_bf16_f32 v32, v32, v33
	v_cvt_pk_bf16_f32 v33, v34, v35
	v_cvt_pk_bf16_f32 v28, v28, v29
	v_cvt_pk_bf16_f32 v29, v30, v31
	v_cvt_pk_bf16_f32 v24, v24, v25
	v_cvt_pk_bf16_f32 v25, v26, v27
	v_cvt_pk_bf16_f32 v20, v20, v21
	v_cvt_pk_bf16_f32 v21, v22, v23
	global_store_dwordx2 v176, v[32:33], s[2:3]
	global_store_dwordx2 v176, v[28:29], s[2:3] offset:32
	global_store_dwordx2 v176, v[24:25], s[2:3] offset:256
	global_store_dwordx2 v176, v[20:21], s[2:3] offset:288
	s_waitcnt vmcnt(8) lgkmcnt(0)
	v_lshlrev_b32_e32 v214, 16, v206
	v_and_b32_e32 v215, 0xffff0000, v206
	v_lshlrev_b32_e32 v216, 16, v207
	v_and_b32_e32 v217, 0xffff0000, v207
	v_lshlrev_b32_e32 v218, 16, v208
	v_and_b32_e32 v219, 0xffff0000, v208
	v_lshlrev_b32_e32 v220, 16, v209
	v_and_b32_e32 v221, 0xffff0000, v209
	v_lshlrev_b32_e32 v222, 16, v210
	v_and_b32_e32 v223, 0xffff0000, v210
	v_lshlrev_b32_e32 v224, 16, v211
	v_and_b32_e32 v225, 0xffff0000, v211
	v_lshlrev_b32_e32 v226, 16, v212
	v_and_b32_e32 v227, 0xffff0000, v212
	v_lshlrev_b32_e32 v228, 16, v213
	v_and_b32_e32 v229, 0xffff0000, v213
	v_mul_f32_e32 v214, 0xbfb8aa3b, v214
	v_mul_f32_e32 v215, 0xbfb8aa3b, v215
	v_mul_f32_e32 v216, 0xbfb8aa3b, v216
	v_mul_f32_e32 v217, 0xbfb8aa3b, v217
	v_mul_f32_e32 v218, 0xbfb8aa3b, v218
	v_mul_f32_e32 v219, 0xbfb8aa3b, v219
	v_mul_f32_e32 v220, 0xbfb8aa3b, v220
	v_mul_f32_e32 v221, 0xbfb8aa3b, v221
	v_mul_f32_e32 v222, 0xbfb8aa3b, v222
	v_mul_f32_e32 v223, 0xbfb8aa3b, v223
	v_mul_f32_e32 v224, 0xbfb8aa3b, v224
	v_mul_f32_e32 v225, 0xbfb8aa3b, v225
	v_mul_f32_e32 v226, 0xbfb8aa3b, v226
	v_mul_f32_e32 v227, 0xbfb8aa3b, v227
	v_mul_f32_e32 v228, 0xbfb8aa3b, v228
	v_mul_f32_e32 v229, 0xbfb8aa3b, v229
	v_exp_f32_e32 v214, v214
	v_exp_f32_e32 v215, v215
	v_exp_f32_e32 v216, v216
	v_exp_f32_e32 v217, v217
	v_exp_f32_e32 v218, v218
	v_exp_f32_e32 v219, v219
	v_exp_f32_e32 v220, v220
	v_exp_f32_e32 v221, v221
	v_exp_f32_e32 v222, v222
	v_exp_f32_e32 v223, v223
	v_exp_f32_e32 v224, v224
	v_exp_f32_e32 v225, v225
	v_exp_f32_e32 v226, v226
	v_exp_f32_e32 v227, v227
	v_exp_f32_e32 v228, v228
	v_exp_f32_e32 v229, v229
	v_min_f32_e32 v214, 0x7149f2ca, v214
	v_min_f32_e32 v215, 0x7149f2ca, v215
	v_min_f32_e32 v216, 0x7149f2ca, v216
	v_min_f32_e32 v217, 0x7149f2ca, v217
	v_min_f32_e32 v218, 0x7149f2ca, v218
	v_min_f32_e32 v219, 0x7149f2ca, v219
	v_min_f32_e32 v220, 0x7149f2ca, v220
	v_min_f32_e32 v221, 0x7149f2ca, v221
	v_min_f32_e32 v222, 0x7149f2ca, v222
	v_min_f32_e32 v223, 0x7149f2ca, v223
	v_min_f32_e32 v224, 0x7149f2ca, v224
	v_min_f32_e32 v225, 0x7149f2ca, v225
	v_min_f32_e32 v226, 0x7149f2ca, v226
	v_min_f32_e32 v227, 0x7149f2ca, v227
	v_min_f32_e32 v228, 0x7149f2ca, v228
	v_min_f32_e32 v229, 0x7149f2ca, v229
	v_add_f32_e32 v214, 1.0, v214
	v_add_f32_e32 v215, 1.0, v215
	v_add_f32_e32 v216, 1.0, v216
	v_add_f32_e32 v217, 1.0, v217
	v_add_f32_e32 v218, 1.0, v218
	v_add_f32_e32 v219, 1.0, v219
	v_add_f32_e32 v220, 1.0, v220
	v_add_f32_e32 v221, 1.0, v221
	v_add_f32_e32 v222, 1.0, v222
	v_add_f32_e32 v223, 1.0, v223
	v_add_f32_e32 v224, 1.0, v224
	v_add_f32_e32 v225, 1.0, v225
	v_add_f32_e32 v226, 1.0, v226
	v_add_f32_e32 v227, 1.0, v227
	v_add_f32_e32 v228, 1.0, v228
	v_add_f32_e32 v229, 1.0, v229
	v_rcp_f32_e32 v214, v214
	v_rcp_f32_e32 v215, v215
	v_rcp_f32_e32 v216, v216
	v_rcp_f32_e32 v217, v217
	v_rcp_f32_e32 v218, v218
	v_rcp_f32_e32 v219, v219
	v_rcp_f32_e32 v220, v220
	v_rcp_f32_e32 v221, v221
	v_rcp_f32_e32 v222, v222
	v_rcp_f32_e32 v223, v223
	v_rcp_f32_e32 v224, v224
	v_rcp_f32_e32 v225, v225
	v_rcp_f32_e32 v226, v226
	v_rcp_f32_e32 v227, v227
	v_rcp_f32_e32 v228, v228
	v_rcp_f32_e32 v229, v229
	v_add_u32_e32 v176, 0x58000, v172
	v_mul_f32_e32 v16, v16, v214
	v_mul_f32_e32 v17, v17, v215
	v_mul_f32_e32 v18, v18, v216
	v_mul_f32_e32 v19, v19, v217
	v_mul_f32_e32 v12, v12, v218
	v_mul_f32_e32 v13, v13, v219
	v_mul_f32_e32 v14, v14, v220
	v_mul_f32_e32 v15, v15, v221
	v_mul_f32_e32 v8, v8, v222
	v_mul_f32_e32 v9, v9, v223
	v_mul_f32_e32 v10, v10, v224
	v_mul_f32_e32 v11, v11, v225
	v_mul_f32_e32 v4, v4, v226
	v_mul_f32_e32 v5, v5, v227
	v_mul_f32_e32 v6, v6, v228
	v_mul_f32_e32 v7, v7, v229
	v_cvt_pk_bf16_f32 v16, v16, v17
	v_cvt_pk_bf16_f32 v17, v18, v19
	v_cvt_pk_bf16_f32 v12, v12, v13
	v_cvt_pk_bf16_f32 v13, v14, v15
	v_cvt_pk_bf16_f32 v8, v8, v9
	v_cvt_pk_bf16_f32 v9, v10, v11
	v_cvt_pk_bf16_f32 v4, v4, v5
	v_cvt_pk_bf16_f32 v5, v6, v7
	global_store_dwordx2 v176, v[16:17], s[2:3]
	global_store_dwordx2 v176, v[12:13], s[2:3] offset:32
	global_store_dwordx2 v176, v[8:9], s[2:3] offset:256
	global_store_dwordx2 v176, v[4:5], s[2:3] offset:288
	s_andn2_b64 vcc, exec, s[6:7]
	s_mov_b64 s[6:7], -1
	s_movk_i32 s13, 0x1320
	s_cbranch_vccnz .LBB0_1071
	s_andn2_b64 vcc, exec, s[0:1]
	s_cbranch_vccnz .LBB0_1070
	s_barrier
	s_branch .LBB0_1070
